# mini_ring (sample-row unit) consume step rewritten by hand: ten ds_read_b128 in flight then 8 MFMAs behind counted lgkmcnt waits, main-loop block of in-proj x2, FFN-up, FFN-down instances
# speedup vs baseline: 1.0139x; 1.0139x over previous
; #define MR_ISSUE(c) do { const unsigned sb_ = ldw + (unsigned)(((c) & (NS - 1)) * SLOT); glds16_m(src[0] + (size_t)(c) * 128, sb_); glds16_m(src[1] + (size_t)(c) * 128, sb_ + 8192u); } while (0)
; template <class Epi>
; __device__ __forceinline__ void mini_ring(PG8_LAS unsigned char* lds, const bf16_t* A, const bf16_t* Bt, int K, const Epi& E, int mu, int wave_u) {
;     ...
;     const int nmain = nchunk - PD;
; #pragma unroll 1
;     for (int c = 0; c < nmain; ++c) {
;         MR_ISSUE(c + PD);
;         asm volatile("s_waitcnt vmcnt(12)" ::: "memory"); __builtin_amdgcn_s_barrier(); asm volatile("" ::: "memory");
;         MR_CONSUME(c);
.LBB0_201:
	s_add_i32 s10, s1, 0x18000
	s_and_b32 s10, s10, 0x1c000
	s_add_i32 s10, s10, s0
	s_mov_b32 s11, m0
	s_mov_b32 m0, s10
	s_nop 0
	global_load_lds_dwordx4 v[22:23], off
	s_mov_b32 m0, s11
	s_addk_i32 s10, 0x2000
	s_mov_b32 s11, m0
	s_mov_b32 m0, s10
	s_nop 0
	global_load_lds_dwordx4 v[20:21], off
	s_mov_b32 m0, s11
	s_waitcnt vmcnt(12)
	s_barrier
	v_cndmask_b32_e64 v0, 0, 1, s[16:17]
	v_cmp_ne_u32_e64 s[10:11], 1, v0
	s_andn2_b64 vcc, exec, s[16:17]
	s_cbranch_vccnz .LBB0_200
	s_and_b32 s24, s1, 0x1c000
	v_add_u32_e32 v0, s24, v28
	v_add_u32_e32 v29, v0, v26
	v_add_u32_e32 v2, s24, v27
	v_add_u32_e32 v3, v2, v26
	v_add_u32_e32 v0, v0, v25
	v_add_u32_e32 v2, v2, v25
	ds_read_b128 v[34:37], v3
	ds_read_b128 v[30:33], v29 offset:8192
	ds_read_b128 v[44:47], v29 offset:10240
	ds_read_b128 v[48:51], v29 offset:12288
	ds_read_b128 v[56:59], v29 offset:14336
	ds_read_b128 v[38:41], v2
	ds_read_b128 v[64:67], v0 offset:8192
	ds_read_b128 v[68:71], v0 offset:10240
	s_waitcnt lgkmcnt(6)
	v_mfma_f32_16x16x32_bf16 v[16:19], v[30:33], v[34:37], v[16:19]
	ds_read_b128 v[30:33], v0 offset:12288
	s_waitcnt lgkmcnt(6)
	v_mfma_f32_16x16x32_bf16 v[12:15], v[44:47], v[34:37], v[12:15]
	ds_read_b128 v[44:47], v0 offset:14336
	s_waitcnt lgkmcnt(6)
	v_mfma_f32_16x16x32_bf16 v[4:7], v[48:51], v[34:37], v[4:7]
	s_waitcnt lgkmcnt(5)
	v_mfma_f32_16x16x32_bf16 v[8:11], v[56:59], v[34:37], v[8:11]
	s_waitcnt lgkmcnt(3)
	v_mfma_f32_16x16x32_bf16 v[16:19], v[64:67], v[38:41], v[16:19]
	s_waitcnt lgkmcnt(2)
	v_mfma_f32_16x16x32_bf16 v[12:15], v[68:71], v[38:41], v[12:15]
	s_waitcnt lgkmcnt(1)
	v_mfma_f32_16x16x32_bf16 v[4:7], v[30:33], v[38:41], v[4:7]
	s_waitcnt lgkmcnt(0)
	v_mfma_f32_16x16x32_bf16 v[8:11], v[44:47], v[38:41], v[8:11]
	s_branch .LBB0_200

; #define MR_ISSUE(c) do { const unsigned sb_ = ldw + (unsigned)(((c) & (NS - 1)) * SLOT); glds16_m(src[0] + (size_t)(c) * 128, sb_); glds16_m(src[1] + (size_t)(c) * 128, sb_ + 8192u); } while (0)
; template <class Epi>
; __device__ __forceinline__ void mini_ring(PG8_LAS unsigned char* lds, const bf16_t* A, const bf16_t* Bt, int K, const Epi& E, int mu, int wave_u) {
;     ...
;     const int nmain = nchunk - PD;
; #pragma unroll 1
;     for (int c = 0; c < nmain; ++c) {
;         MR_ISSUE(c + PD);
;         asm volatile("s_waitcnt vmcnt(12)" ::: "memory"); __builtin_amdgcn_s_barrier(); asm volatile("" ::: "memory");
;         MR_CONSUME(c);
.LBB0_351:
	s_add_i32 s10, s1, 0x18000
	s_and_b32 s10, s10, 0x1c000
	s_add_i32 s10, s10, s0
	s_mov_b32 s11, m0
	s_mov_b32 m0, s10
	s_nop 0
	global_load_lds_dwordx4 v[14:15], off
	s_mov_b32 m0, s11
	s_addk_i32 s10, 0x2000
	s_mov_b32 s11, m0
	s_mov_b32 m0, s10
	s_nop 0
	global_load_lds_dwordx4 v[12:13], off
	s_mov_b32 m0, s11
	s_waitcnt vmcnt(12)
	s_barrier
	v_cndmask_b32_e64 v0, 0, 1, s[14:15]
	v_cmp_ne_u32_e64 s[10:11], 1, v0
	s_andn2_b64 vcc, exec, s[14:15]
	s_cbranch_vccnz .LBB0_350
	s_and_b32 s23, s1, 0x1c000
	v_add_u32_e32 v0, s23, v20
	v_add_u32_e32 v21, v0, v18
	v_add_u32_e32 v2, s23, v19
	v_add_u32_e32 v3, v2, v18
	v_add_u32_e32 v0, v0, v17
	v_add_u32_e32 v2, v2, v17
	ds_read_b128 v[32:35], v3
	ds_read_b128 v[22:25], v21 offset:8192
	ds_read_b128 v[40:43], v21 offset:10240
	ds_read_b128 v[44:47], v21 offset:12288
	ds_read_b128 v[64:67], v21 offset:14336
	ds_read_b128 v[36:39], v2
	s_waitcnt lgkmcnt(4)
	v_mfma_f32_16x16x32_bf16 v[48:51], v[22:25], v[32:35], v[48:51]
	ds_read_b128 v[22:25], v0 offset:8192
	s_waitcnt lgkmcnt(4)
	v_mfma_f32_16x16x32_bf16 v[28:31], v[40:43], v[32:35], v[28:31]
	ds_read_b128 v[40:43], v0 offset:10240
	s_waitcnt lgkmcnt(4)
	v_mfma_f32_16x16x32_bf16 v[4:7], v[44:47], v[32:35], v[4:7]
	ds_read_b128 v[44:47], v0 offset:12288
	s_waitcnt lgkmcnt(4)
	v_mfma_f32_16x16x32_bf16 v[8:11], v[64:67], v[32:35], v[8:11]
	ds_read_b128 v[64:67], v0 offset:14336
	s_waitcnt lgkmcnt(3)
	v_mfma_f32_16x16x32_bf16 v[48:51], v[22:25], v[36:39], v[48:51]
	s_waitcnt lgkmcnt(2)
	v_mfma_f32_16x16x32_bf16 v[28:31], v[40:43], v[36:39], v[28:31]
	s_waitcnt lgkmcnt(1)
	v_mfma_f32_16x16x32_bf16 v[4:7], v[44:47], v[36:39], v[4:7]
	s_waitcnt lgkmcnt(0)
	v_mfma_f32_16x16x32_bf16 v[8:11], v[64:67], v[36:39], v[8:11]
	s_branch .LBB0_350

; #define MR_ISSUE(c) do { const unsigned sb_ = ldw + (unsigned)(((c) & (NS - 1)) * SLOT); glds16_m(src[0] + (size_t)(c) * 128, sb_); glds16_m(src[1] + (size_t)(c) * 128, sb_ + 8192u); } while (0)
; template <class Epi>
; __device__ __forceinline__ void mini_ring(PG8_LAS unsigned char* lds, const bf16_t* A, const bf16_t* Bt, int K, const Epi& E, int mu, int wave_u) {
;     ...
;     const int nmain = nchunk - PD;
; #pragma unroll 1
;     for (int c = 0; c < nmain; ++c) {
;         MR_ISSUE(c + PD);
;         asm volatile("s_waitcnt vmcnt(12)" ::: "memory"); __builtin_amdgcn_s_barrier(); asm volatile("" ::: "memory");
;         MR_CONSUME(c);
.LBB0_1215:
	s_add_i32 s2, s1, 0x18000
	s_and_b32 s2, s2, 0x1c000
	s_add_i32 s2, s2, s0
	s_mov_b32 s10, m0
	s_mov_b32 m0, s2
	s_nop 0
	global_load_lds_dwordx4 v[16:17], off
	s_mov_b32 m0, s10
	s_addk_i32 s2, 0x2000
	s_mov_b32 s10, m0
	s_mov_b32 m0, s2
	s_nop 0
	global_load_lds_dwordx4 v[14:15], off
	s_mov_b32 m0, s10
	s_waitcnt vmcnt(12)
	s_barrier
	v_cndmask_b32_e64 v0, 0, 1, s[16:17]
	v_cmp_ne_u32_e64 s[10:11], 1, v0
	s_andn2_b64 vcc, exec, s[16:17]
	s_cbranch_vccnz .LBB0_1214
	s_and_b32 s2, s1, 0x1c000
	s_waitcnt lgkmcnt(0)
	v_add_u32_e32 v0, s2, v22
	v_add_u32_e32 v23, v0, v20
	v_add_u32_e32 v40, s2, v21
	v_add_u32_e32 v28, v40, v20
	v_add_u32_e32 v0, v0, v19
	v_add_u32_e32 v40, v40, v19
	ds_read_b128 v[28:31], v28
	ds_read_b128 v[24:27], v23 offset:8192
	ds_read_b128 v[36:39], v23 offset:10240
	ds_read_b128 v[52:55], v23 offset:12288
	ds_read_b128 v[60:63], v23 offset:14336
	ds_read_b128 v[32:35], v40
	ds_read_b128 v[64:67], v0 offset:8192
	s_waitcnt lgkmcnt(5)
	v_mfma_f32_16x16x32_bf16 v[46:49], v[24:27], v[28:31], v[46:49]
	ds_read_b128 v[24:27], v0 offset:10240
	s_waitcnt lgkmcnt(5)
	v_mfma_f32_16x16x32_bf16 v[10:13], v[36:39], v[28:31], v[10:13]
	ds_read_b128 v[36:39], v0 offset:12288
	s_waitcnt lgkmcnt(5)
	v_mfma_f32_16x16x32_bf16 v[6:9], v[52:55], v[28:31], v[6:9]
	ds_read_b128 v[52:55], v0 offset:14336
	s_waitcnt lgkmcnt(5)
	v_mfma_f32_16x16x32_bf16 v[2:5], v[60:63], v[28:31], v[2:5]
	s_waitcnt lgkmcnt(3)
	v_mfma_f32_16x16x32_bf16 v[46:49], v[64:67], v[32:35], v[46:49]
	s_waitcnt lgkmcnt(2)
	v_mfma_f32_16x16x32_bf16 v[10:13], v[24:27], v[32:35], v[10:13]
	s_waitcnt lgkmcnt(1)
	v_mfma_f32_16x16x32_bf16 v[6:9], v[36:39], v[32:35], v[6:9]
	s_waitcnt lgkmcnt(0)
	v_mfma_f32_16x16x32_bf16 v[2:5], v[52:55], v[32:35], v[2:5]
	s_branch .LBB0_1214

; #define MR_ISSUE(c) do { const unsigned sb_ = ldw + (unsigned)(((c) & (NS - 1)) * SLOT); glds16_m(src[0] + (size_t)(c) * 128, sb_); glds16_m(src[1] + (size_t)(c) * 128, sb_ + 8192u); } while (0)
; template <class Epi>
; __device__ __forceinline__ void mini_ring(PG8_LAS unsigned char* lds, const bf16_t* A, const bf16_t* Bt, int K, const Epi& E, int mu, int wave_u) {
;     ...
;     const int nmain = nchunk - PD;
; #pragma unroll 1
;     for (int c = 0; c < nmain; ++c) {
;         MR_ISSUE(c + PD);
;         asm volatile("s_waitcnt vmcnt(12)" ::: "memory"); __builtin_amdgcn_s_barrier(); asm volatile("" ::: "memory");
;         MR_CONSUME(c);
.LBB0_1468:
	s_add_i32 s10, s1, 0x18000
	s_and_b32 s10, s10, 0x1c000
	s_add_i32 s10, s10, s0
	s_mov_b32 s11, m0
	s_mov_b32 m0, s10
	s_nop 0
	global_load_lds_dwordx4 v[6:7], off
	s_mov_b32 m0, s11
	s_addk_i32 s10, 0x2000
	s_mov_b32 s11, m0
	s_mov_b32 m0, s10
	s_nop 0
	global_load_lds_dwordx4 v[4:5], off
	s_mov_b32 m0, s11
	s_waitcnt vmcnt(12)
	s_barrier
	v_cndmask_b32_e64 v0, 0, 1, s[12:13]
	v_cmp_ne_u32_e64 s[10:11], 1, v0
	s_andn2_b64 vcc, exec, s[12:13]
	s_cbranch_vccnz .LBB0_1467
	s_and_b32 s17, s1, 0x1c000
	v_add_u32_e32 v0, s17, v12
	v_add_u32_e32 v2, v0, v9
	v_add_u32_e32 v3, s17, v11
	v_add_u32_e32 v13, v3, v9
	v_add_u32_e32 v0, v0, v10
	v_add_u32_e32 v3, v3, v10
	ds_read_b128 v[44:47], v13
	ds_read_b128 v[48:51], v2 offset:8192
	ds_read_b128 v[52:55], v2 offset:10240
	ds_read_b128 v[56:59], v2 offset:12288
	ds_read_b128 v[60:63], v2 offset:14336
	ds_read_b128 v[64:67], v3
	ds_read_b128 v[68:71], v0 offset:8192
	ds_read_b128 v[72:75], v0 offset:10240
	ds_read_b128 v[76:79], v0 offset:12288
	ds_read_b128 v[14:17], v0 offset:14336
	s_waitcnt lgkmcnt(8)
	v_mfma_f32_16x16x32_bf16 v[30:33], v[48:51], v[44:47], v[30:33]
	s_waitcnt lgkmcnt(7)
	v_mfma_f32_16x16x32_bf16 v[34:37], v[52:55], v[44:47], v[34:37]
	s_waitcnt lgkmcnt(6)
	v_mfma_f32_16x16x32_bf16 v[18:21], v[56:59], v[44:47], v[18:21]
	s_waitcnt lgkmcnt(5)
	v_mfma_f32_16x16x32_bf16 v[22:25], v[60:63], v[44:47], v[22:25]
	s_waitcnt lgkmcnt(3)
	v_mfma_f32_16x16x32_bf16 v[30:33], v[68:71], v[64:67], v[30:33]
	s_waitcnt lgkmcnt(2)
	v_mfma_f32_16x16x32_bf16 v[34:37], v[72:75], v[64:67], v[34:37]
	s_waitcnt lgkmcnt(1)
	v_mfma_f32_16x16x32_bf16 v[18:21], v[76:79], v[64:67], v[18:21]
	s_waitcnt lgkmcnt(0)
	v_mfma_f32_16x16x32_bf16 v[22:25], v[14:17], v[64:67], v[22:25]
	s_branch .LBB0_1467
